# GEMM accumulator zeroing per tile with 63 v_mov_b64 instead of 126 v_mov_b32 (13 GEMM bodies)
# speedup vs baseline: 1.0061x; 1.0016x over previous
.LBB0_271:
	s_ashr_i32 s37, s36, 31
	s_lshl_b64 s[38:39], s[36:37], 19
	s_add_u32 s38, s58, s38
	s_addc_u32 s39, s59, s39
	s_and_b64 s[40:41], s[4:5], exec
	s_cselect_b32 s37, s39, s61
	s_cselect_b32 s43, s38, s60
	s_ashr_i32 s35, s34, 31
	s_lshl_b64 s[40:41], s[34:35], 19
	s_add_u32 s40, s66, s40
	s_addc_u32 s41, s67, s41
	s_and_b64 s[64:65], s[4:5], exec
	s_cselect_b32 s35, s41, s63
	s_cselect_b32 s55, s40, s62
	s_add_u32 s60, s60, 0x40080
	s_addc_u32 s61, s61, 0
	s_add_u32 s84, s62, 0x100
	v_mov_b32_e32 v0, 0
	s_addc_u32 s85, s63, 0
	s_mov_b32 s86, -2
	v_mov_b32_e32 v1, v0
	v_mov_b64_e32 v[2:3], 0
	v_mov_b64_e32 v[4:5], 0
	v_mov_b64_e32 v[6:7], 0
	v_mov_b64_e32 v[8:9], 0
	v_mov_b64_e32 v[10:11], 0
	v_mov_b64_e32 v[16:17], 0
	v_mov_b64_e32 v[18:19], 0
	v_mov_b64_e32 v[24:25], 0
	v_mov_b64_e32 v[26:27], 0
	v_mov_b64_e32 v[32:33], 0
	v_mov_b64_e32 v[34:35], 0
	v_mov_b64_e32 v[40:41], 0
	v_mov_b64_e32 v[42:43], 0
	v_mov_b64_e32 v[48:49], 0
	v_mov_b64_e32 v[50:51], 0
	v_mov_b64_e32 v[12:13], 0
	v_mov_b64_e32 v[14:15], 0
	v_mov_b64_e32 v[20:21], 0
	v_mov_b64_e32 v[22:23], 0
	v_mov_b64_e32 v[28:29], 0
	v_mov_b64_e32 v[30:31], 0
	v_mov_b64_e32 v[36:37], 0
	v_mov_b64_e32 v[38:39], 0
	v_mov_b64_e32 v[44:45], 0
	v_mov_b64_e32 v[46:47], 0
	v_mov_b64_e32 v[52:53], 0
	v_mov_b64_e32 v[54:55], 0
	v_mov_b64_e32 v[56:57], 0
	v_mov_b64_e32 v[58:59], 0
	v_mov_b64_e32 v[60:61], 0
	v_mov_b64_e32 v[62:63], 0
	v_mov_b64_e32 v[64:65], 0
	v_mov_b64_e32 v[66:67], 0
	v_mov_b64_e32 v[68:69], 0
	v_mov_b64_e32 v[70:71], 0
	v_mov_b64_e32 v[72:73], 0
	v_mov_b64_e32 v[74:75], 0
	v_mov_b64_e32 v[80:81], 0
	v_mov_b64_e32 v[82:83], 0
	v_mov_b64_e32 v[88:89], 0
	v_mov_b64_e32 v[90:91], 0
	v_mov_b64_e32 v[96:97], 0
	v_mov_b64_e32 v[98:99], 0
	v_mov_b64_e32 v[104:105], 0
	v_mov_b64_e32 v[106:107], 0
	v_mov_b64_e32 v[112:113], 0
	v_mov_b64_e32 v[114:115], 0
	v_mov_b64_e32 v[76:77], 0
	v_mov_b64_e32 v[78:79], 0
	v_mov_b64_e32 v[84:85], 0
	v_mov_b64_e32 v[86:87], 0
	v_mov_b64_e32 v[92:93], 0
	v_mov_b64_e32 v[94:95], 0
	v_mov_b64_e32 v[100:101], 0
	v_mov_b64_e32 v[102:103], 0
	v_mov_b64_e32 v[108:109], 0
	v_mov_b64_e32 v[110:111], 0
	v_mov_b64_e32 v[116:117], 0
	v_mov_b64_e32 v[118:119], 0
	v_mov_b64_e32 v[120:121], 0
	v_mov_b64_e32 v[122:123], 0
	v_mov_b64_e32 v[124:125], 0
	v_mov_b64_e32 v[126:127], 0

.LBB0_301:
	s_ashr_i32 s27, s26, 31
	s_lshl_b64 s[28:29], s[26:27], 19
	s_add_u32 s28, s43, s28
	s_addc_u32 s29, s52, s29
	s_and_b64 s[30:31], s[4:5], exec
	s_cselect_b32 s27, s29, s37
	s_cselect_b32 s55, s28, s36
	s_ashr_i32 s25, s24, 31
	s_lshl_b64 s[30:31], s[24:25], 19
	s_add_u32 s30, s58, s30
	s_addc_u32 s31, s59, s31
	s_and_b64 s[40:41], s[4:5], exec
	s_cselect_b32 s25, s31, s39
	s_cselect_b32 s72, s30, s38
	s_add_u32 s36, s36, 0x40080
	s_addc_u32 s37, s37, 0
	s_add_u32 s73, s38, 0x100
	v_mov_b32_e32 v0, 0
	s_addc_u32 s74, s39, 0
	s_mov_b32 s75, -2
	v_mov_b32_e32 v1, v0
	v_mov_b64_e32 v[2:3], 0
	v_mov_b64_e32 v[4:5], 0
	v_mov_b64_e32 v[6:7], 0
	v_mov_b64_e32 v[8:9], 0
	v_mov_b64_e32 v[10:11], 0
	v_mov_b64_e32 v[16:17], 0
	v_mov_b64_e32 v[18:19], 0
	v_mov_b64_e32 v[24:25], 0
	v_mov_b64_e32 v[26:27], 0
	v_mov_b64_e32 v[32:33], 0
	v_mov_b64_e32 v[34:35], 0
	v_mov_b64_e32 v[40:41], 0
	v_mov_b64_e32 v[42:43], 0
	v_mov_b64_e32 v[48:49], 0
	v_mov_b64_e32 v[50:51], 0
	v_mov_b64_e32 v[12:13], 0
	v_mov_b64_e32 v[14:15], 0
	v_mov_b64_e32 v[20:21], 0
	v_mov_b64_e32 v[22:23], 0
	v_mov_b64_e32 v[28:29], 0
	v_mov_b64_e32 v[30:31], 0
	v_mov_b64_e32 v[36:37], 0
	v_mov_b64_e32 v[38:39], 0
	v_mov_b64_e32 v[44:45], 0
	v_mov_b64_e32 v[46:47], 0
	v_mov_b64_e32 v[52:53], 0
	v_mov_b64_e32 v[54:55], 0
	v_mov_b64_e32 v[56:57], 0
	v_mov_b64_e32 v[58:59], 0
	v_mov_b64_e32 v[60:61], 0
	v_mov_b64_e32 v[62:63], 0
	v_mov_b64_e32 v[64:65], 0
	v_mov_b64_e32 v[66:67], 0
	v_mov_b64_e32 v[68:69], 0
	v_mov_b64_e32 v[70:71], 0
	v_mov_b64_e32 v[72:73], 0
	v_mov_b64_e32 v[74:75], 0
	v_mov_b64_e32 v[80:81], 0
	v_mov_b64_e32 v[82:83], 0
	v_mov_b64_e32 v[88:89], 0
	v_mov_b64_e32 v[90:91], 0
	v_mov_b64_e32 v[96:97], 0
	v_mov_b64_e32 v[98:99], 0
	v_mov_b64_e32 v[104:105], 0
	v_mov_b64_e32 v[106:107], 0
	v_mov_b64_e32 v[112:113], 0
	v_mov_b64_e32 v[114:115], 0
	v_mov_b64_e32 v[76:77], 0
	v_mov_b64_e32 v[78:79], 0
	v_mov_b64_e32 v[84:85], 0
	v_mov_b64_e32 v[86:87], 0
	v_mov_b64_e32 v[92:93], 0
	v_mov_b64_e32 v[94:95], 0
	v_mov_b64_e32 v[100:101], 0
	v_mov_b64_e32 v[102:103], 0
	v_mov_b64_e32 v[108:109], 0
	v_mov_b64_e32 v[110:111], 0
	v_mov_b64_e32 v[116:117], 0
	v_mov_b64_e32 v[118:119], 0
	v_mov_b64_e32 v[120:121], 0
	v_mov_b64_e32 v[122:123], 0
	v_mov_b64_e32 v[124:125], 0
	v_mov_b64_e32 v[126:127], 0

.LBB0_699:
	s_ashr_i32 s25, s24, 31
	s_lshl_b64 s[26:27], s[24:25], 19
	s_add_u32 s26, s58, s26
	s_addc_u32 s27, s59, s27
	s_and_b64 s[28:29], s[4:5], exec
	s_cselect_b32 s25, s27, s35
	s_cselect_b32 s55, s26, s34
	s_ashr_i32 s23, s22, 31
	s_lshl_b64 s[28:29], s[22:23], 19
	s_add_u32 s28, s43, s28
	s_addc_u32 s29, s52, s29
	s_and_b64 s[40:41], s[4:5], exec
	s_cselect_b32 s23, s29, s39
	s_cselect_b32 s72, s28, s38
	s_add_u32 s34, s34, 0x40080
	s_addc_u32 s35, s35, 0
	s_add_u32 s73, s38, 0x100
	v_mov_b32_e32 v0, 0
	s_addc_u32 s74, s39, 0
	s_mov_b32 s75, -2
	v_mov_b32_e32 v1, v0
	v_mov_b64_e32 v[2:3], 0
	v_mov_b64_e32 v[4:5], 0
	v_mov_b64_e32 v[6:7], 0
	v_mov_b64_e32 v[8:9], 0
	v_mov_b64_e32 v[10:11], 0
	v_mov_b64_e32 v[16:17], 0
	v_mov_b64_e32 v[18:19], 0
	v_mov_b64_e32 v[24:25], 0
	v_mov_b64_e32 v[26:27], 0
	v_mov_b64_e32 v[32:33], 0
	v_mov_b64_e32 v[34:35], 0
	v_mov_b64_e32 v[40:41], 0
	v_mov_b64_e32 v[42:43], 0
	v_mov_b64_e32 v[48:49], 0
	v_mov_b64_e32 v[50:51], 0
	v_mov_b64_e32 v[12:13], 0
	v_mov_b64_e32 v[14:15], 0
	v_mov_b64_e32 v[20:21], 0
	v_mov_b64_e32 v[22:23], 0
	v_mov_b64_e32 v[28:29], 0
	v_mov_b64_e32 v[30:31], 0
	v_mov_b64_e32 v[36:37], 0
	v_mov_b64_e32 v[38:39], 0
	v_mov_b64_e32 v[44:45], 0
	v_mov_b64_e32 v[46:47], 0
	v_mov_b64_e32 v[52:53], 0
	v_mov_b64_e32 v[54:55], 0
	v_mov_b64_e32 v[56:57], 0
	v_mov_b64_e32 v[58:59], 0
	v_mov_b64_e32 v[60:61], 0
	v_mov_b64_e32 v[62:63], 0
	v_mov_b64_e32 v[64:65], 0
	v_mov_b64_e32 v[66:67], 0
	v_mov_b64_e32 v[68:69], 0
	v_mov_b64_e32 v[70:71], 0
	v_mov_b64_e32 v[72:73], 0
	v_mov_b64_e32 v[74:75], 0
	v_mov_b64_e32 v[80:81], 0
	v_mov_b64_e32 v[82:83], 0
	v_mov_b64_e32 v[88:89], 0
	v_mov_b64_e32 v[90:91], 0
	v_mov_b64_e32 v[96:97], 0
	v_mov_b64_e32 v[98:99], 0
	v_mov_b64_e32 v[104:105], 0
	v_mov_b64_e32 v[106:107], 0
	v_mov_b64_e32 v[112:113], 0
	v_mov_b64_e32 v[114:115], 0
	v_mov_b64_e32 v[76:77], 0
	v_mov_b64_e32 v[78:79], 0
	v_mov_b64_e32 v[84:85], 0
	v_mov_b64_e32 v[86:87], 0
	v_mov_b64_e32 v[92:93], 0
	v_mov_b64_e32 v[94:95], 0
	v_mov_b64_e32 v[100:101], 0
	v_mov_b64_e32 v[102:103], 0
	v_mov_b64_e32 v[108:109], 0
	v_mov_b64_e32 v[110:111], 0
	v_mov_b64_e32 v[116:117], 0
	v_mov_b64_e32 v[118:119], 0
	v_mov_b64_e32 v[120:121], 0
	v_mov_b64_e32 v[122:123], 0
	v_mov_b64_e32 v[124:125], 0
	v_mov_b64_e32 v[126:127], 0

.LBB0_836:
	s_ashr_i32 s25, s24, 31
	s_lshl_b64 s[26:27], s[24:25], 19
	s_add_u32 s26, s58, s26
	s_addc_u32 s27, s59, s27
	s_and_b64 s[28:29], s[4:5], exec
	s_cselect_b32 s25, s27, s35
	s_cselect_b32 s54, s26, s34
	s_ashr_i32 s23, s22, 31
	s_lshl_b64 s[28:29], s[22:23], 19
	s_add_u32 s28, s61, s28
	s_addc_u32 s29, s62, s29
	s_and_b64 s[42:43], s[4:5], exec
	s_cselect_b32 s23, s29, s41
	s_cselect_b32 s55, s28, s40
	s_add_u32 s34, s34, 0x40080
	s_addc_u32 s35, s35, 0
	s_add_u32 s75, s40, 0x100
	v_mov_b32_e32 v0, 0
	s_addc_u32 s76, s41, 0
	s_mov_b32 s77, -2
	v_mov_b32_e32 v1, v0
	v_mov_b64_e32 v[2:3], 0
	v_mov_b64_e32 v[4:5], 0
	v_mov_b64_e32 v[6:7], 0
	v_mov_b64_e32 v[16:17], 0
	v_mov_b64_e32 v[18:19], 0
	v_mov_b64_e32 v[20:21], 0
	v_mov_b64_e32 v[22:23], 0
	v_mov_b64_e32 v[32:33], 0
	v_mov_b64_e32 v[34:35], 0
	v_mov_b64_e32 v[36:37], 0
	v_mov_b64_e32 v[38:39], 0
	v_mov_b64_e32 v[48:49], 0
	v_mov_b64_e32 v[50:51], 0
	v_mov_b64_e32 v[52:53], 0
	v_mov_b64_e32 v[54:55], 0
	v_mov_b64_e32 v[8:9], 0
	v_mov_b64_e32 v[10:11], 0
	v_mov_b64_e32 v[12:13], 0
	v_mov_b64_e32 v[14:15], 0
	v_mov_b64_e32 v[24:25], 0
	v_mov_b64_e32 v[26:27], 0
	v_mov_b64_e32 v[28:29], 0
	v_mov_b64_e32 v[30:31], 0
	v_mov_b64_e32 v[40:41], 0
	v_mov_b64_e32 v[42:43], 0
	v_mov_b64_e32 v[44:45], 0
	v_mov_b64_e32 v[46:47], 0
	v_mov_b64_e32 v[56:57], 0
	v_mov_b64_e32 v[58:59], 0
	v_mov_b64_e32 v[60:61], 0
	v_mov_b64_e32 v[62:63], 0
	v_mov_b64_e32 v[64:65], 0
	v_mov_b64_e32 v[66:67], 0
	v_mov_b64_e32 v[68:69], 0
	v_mov_b64_e32 v[70:71], 0
	v_mov_b64_e32 v[80:81], 0
	v_mov_b64_e32 v[82:83], 0
	v_mov_b64_e32 v[84:85], 0
	v_mov_b64_e32 v[86:87], 0
	v_mov_b64_e32 v[96:97], 0
	v_mov_b64_e32 v[98:99], 0
	v_mov_b64_e32 v[100:101], 0
	v_mov_b64_e32 v[102:103], 0
	v_mov_b64_e32 v[112:113], 0
	v_mov_b64_e32 v[114:115], 0
	v_mov_b64_e32 v[116:117], 0
	v_mov_b64_e32 v[118:119], 0
	v_mov_b64_e32 v[72:73], 0
	v_mov_b64_e32 v[74:75], 0
	v_mov_b64_e32 v[76:77], 0
	v_mov_b64_e32 v[78:79], 0
	v_mov_b64_e32 v[88:89], 0
	v_mov_b64_e32 v[90:91], 0
	v_mov_b64_e32 v[92:93], 0
	v_mov_b64_e32 v[94:95], 0
	v_mov_b64_e32 v[104:105], 0
	v_mov_b64_e32 v[106:107], 0
	v_mov_b64_e32 v[108:109], 0
	v_mov_b64_e32 v[110:111], 0
	v_mov_b64_e32 v[120:121], 0
	v_mov_b64_e32 v[122:123], 0
	v_mov_b64_e32 v[124:125], 0
	v_mov_b64_e32 v[126:127], 0

.LBB0_915:
	s_ashr_i32 s25, s24, 31
	s_lshl_b64 s[26:27], s[24:25], 21
	s_add_u32 s26, s56, s26
	s_addc_u32 s27, s57, s27
	s_and_b64 s[28:29], s[4:5], exec
	s_cselect_b32 s25, s27, s35
	s_cselect_b32 s55, s26, s34
	s_ashr_i32 s23, s22, 31
	s_lshl_b64 s[28:29], s[22:23], 21
	s_add_u32 s28, s53, s28
	s_addc_u32 s29, s60, s29
	s_and_b64 s[42:43], s[4:5], exec
	s_cselect_b32 s23, s29, s41
	s_cselect_b32 s74, s28, s40
	s_add_u32 s34, s34, 0x100080
	s_addc_u32 s35, s35, 0
	s_add_u32 s75, s40, 0x100
	v_mov_b32_e32 v0, 0
	s_addc_u32 s76, s41, 0
	s_mov_b32 s77, -2
	v_mov_b32_e32 v1, v0
	v_mov_b64_e32 v[2:3], 0
	v_mov_b64_e32 v[4:5], 0
	v_mov_b64_e32 v[6:7], 0
	v_mov_b64_e32 v[8:9], 0
	v_mov_b64_e32 v[10:11], 0
	v_mov_b64_e32 v[16:17], 0
	v_mov_b64_e32 v[18:19], 0
	v_mov_b64_e32 v[24:25], 0
	v_mov_b64_e32 v[26:27], 0
	v_mov_b64_e32 v[32:33], 0
	v_mov_b64_e32 v[34:35], 0
	v_mov_b64_e32 v[40:41], 0
	v_mov_b64_e32 v[42:43], 0
	v_mov_b64_e32 v[48:49], 0
	v_mov_b64_e32 v[50:51], 0
	v_mov_b64_e32 v[12:13], 0
	v_mov_b64_e32 v[14:15], 0
	v_mov_b64_e32 v[20:21], 0
	v_mov_b64_e32 v[22:23], 0
	v_mov_b64_e32 v[28:29], 0
	v_mov_b64_e32 v[30:31], 0
	v_mov_b64_e32 v[36:37], 0
	v_mov_b64_e32 v[38:39], 0
	v_mov_b64_e32 v[44:45], 0
	v_mov_b64_e32 v[46:47], 0
	v_mov_b64_e32 v[52:53], 0
	v_mov_b64_e32 v[54:55], 0
	v_mov_b64_e32 v[56:57], 0
	v_mov_b64_e32 v[58:59], 0
	v_mov_b64_e32 v[60:61], 0
	v_mov_b64_e32 v[62:63], 0
	v_mov_b64_e32 v[64:65], 0
	v_mov_b64_e32 v[66:67], 0
	v_mov_b64_e32 v[68:69], 0
	v_mov_b64_e32 v[70:71], 0
	v_mov_b64_e32 v[72:73], 0
	v_mov_b64_e32 v[74:75], 0
	v_mov_b64_e32 v[80:81], 0
	v_mov_b64_e32 v[82:83], 0
	v_mov_b64_e32 v[88:89], 0
	v_mov_b64_e32 v[90:91], 0
	v_mov_b64_e32 v[96:97], 0
	v_mov_b64_e32 v[98:99], 0
	v_mov_b64_e32 v[104:105], 0
	v_mov_b64_e32 v[106:107], 0
	v_mov_b64_e32 v[112:113], 0
	v_mov_b64_e32 v[114:115], 0
	v_mov_b64_e32 v[76:77], 0
	v_mov_b64_e32 v[78:79], 0
	v_mov_b64_e32 v[84:85], 0
	v_mov_b64_e32 v[86:87], 0
	v_mov_b64_e32 v[92:93], 0
	v_mov_b64_e32 v[94:95], 0
	v_mov_b64_e32 v[100:101], 0
	v_mov_b64_e32 v[102:103], 0
	v_mov_b64_e32 v[108:109], 0
	v_mov_b64_e32 v[110:111], 0
	v_mov_b64_e32 v[116:117], 0
	v_mov_b64_e32 v[118:119], 0
	v_mov_b64_e32 v[120:121], 0
	v_mov_b64_e32 v[122:123], 0
	v_mov_b64_e32 v[124:125], 0
	v_mov_b64_e32 v[126:127], 0

.LBB0_1052:
	s_ashr_i32 s27, s26, 31
	s_lshl_b64 s[28:29], s[26:27], 19
	s_add_u32 s28, s58, s28
	s_addc_u32 s29, s59, s29
	s_and_b64 s[30:31], s[4:5], exec
	s_cselect_b32 s27, s29, s43
	s_cselect_b32 s55, s28, s42
	s_ashr_i32 s25, s24, 31
	s_lshl_b64 s[30:31], s[24:25], 19
	s_add_u32 s30, s53, s30
	s_addc_u32 s31, s64, s31
	s_and_b64 s[62:63], s[4:5], exec
	s_cselect_b32 s25, s31, s61
	s_cselect_b32 s79, s30, s60
	s_add_u32 s42, s42, 0x40080
	s_addc_u32 s43, s43, 0
	s_add_u32 s80, s60, 0x100
	v_mov_b32_e32 v0, 0
	s_addc_u32 s81, s61, 0
	s_mov_b32 s82, -2
	v_mov_b32_e32 v1, v0
	v_mov_b64_e32 v[2:3], 0
	v_mov_b64_e32 v[4:5], 0
	v_mov_b64_e32 v[6:7], 0
	v_mov_b64_e32 v[8:9], 0
	v_mov_b64_e32 v[10:11], 0
	v_mov_b64_e32 v[16:17], 0
	v_mov_b64_e32 v[18:19], 0
	v_mov_b64_e32 v[24:25], 0
	v_mov_b64_e32 v[26:27], 0
	v_mov_b64_e32 v[32:33], 0
	v_mov_b64_e32 v[34:35], 0
	v_mov_b64_e32 v[40:41], 0
	v_mov_b64_e32 v[42:43], 0
	v_mov_b64_e32 v[48:49], 0
	v_mov_b64_e32 v[50:51], 0
	v_mov_b64_e32 v[12:13], 0
	v_mov_b64_e32 v[14:15], 0
	v_mov_b64_e32 v[20:21], 0
	v_mov_b64_e32 v[22:23], 0
	v_mov_b64_e32 v[28:29], 0
	v_mov_b64_e32 v[30:31], 0
	v_mov_b64_e32 v[36:37], 0
	v_mov_b64_e32 v[38:39], 0
	v_mov_b64_e32 v[44:45], 0
	v_mov_b64_e32 v[46:47], 0
	v_mov_b64_e32 v[52:53], 0
	v_mov_b64_e32 v[54:55], 0
	v_mov_b64_e32 v[56:57], 0
	v_mov_b64_e32 v[58:59], 0
	v_mov_b64_e32 v[60:61], 0
	v_mov_b64_e32 v[62:63], 0
	v_mov_b64_e32 v[64:65], 0
	v_mov_b64_e32 v[66:67], 0
	v_mov_b64_e32 v[68:69], 0
	v_mov_b64_e32 v[70:71], 0
	v_mov_b64_e32 v[72:73], 0
	v_mov_b64_e32 v[74:75], 0
	v_mov_b64_e32 v[80:81], 0
	v_mov_b64_e32 v[82:83], 0
	v_mov_b64_e32 v[88:89], 0
	v_mov_b64_e32 v[90:91], 0
	v_mov_b64_e32 v[96:97], 0
	v_mov_b64_e32 v[98:99], 0
	v_mov_b64_e32 v[104:105], 0
	v_mov_b64_e32 v[106:107], 0
	v_mov_b64_e32 v[112:113], 0
	v_mov_b64_e32 v[114:115], 0
	v_mov_b64_e32 v[76:77], 0
	v_mov_b64_e32 v[78:79], 0
	v_mov_b64_e32 v[84:85], 0
	v_mov_b64_e32 v[86:87], 0
	v_mov_b64_e32 v[92:93], 0
	v_mov_b64_e32 v[94:95], 0
	v_mov_b64_e32 v[100:101], 0
	v_mov_b64_e32 v[102:103], 0
	v_mov_b64_e32 v[108:109], 0
	v_mov_b64_e32 v[110:111], 0
	v_mov_b64_e32 v[116:117], 0
	v_mov_b64_e32 v[118:119], 0
	v_mov_b64_e32 v[120:121], 0
	v_mov_b64_e32 v[122:123], 0
	v_mov_b64_e32 v[124:125], 0
	v_mov_b64_e32 v[126:127], 0

.LBB0_1076:
	s_ashr_i32 s27, s26, 31
	s_lshl_b64 s[28:29], s[26:27], 19
	s_add_u32 s28, s40, s28
	s_addc_u32 s29, s41, s29
	s_and_b64 s[30:31], s[4:5], exec
	s_cselect_b32 s27, s29, s43
	s_cselect_b32 s55, s28, s42
	s_ashr_i32 s25, s24, 31
	s_lshl_b64 s[30:31], s[24:25], 19
	s_add_u32 s30, s53, s30
	s_addc_u32 s31, s64, s31
	s_and_b64 s[62:63], s[4:5], exec
	s_cselect_b32 s25, s31, s61
	s_cselect_b32 s79, s30, s60
	s_add_u32 s42, s42, 0x40080
	s_addc_u32 s43, s43, 0
	s_add_u32 s80, s60, 0x100
	v_mov_b32_e32 v0, 0
	s_addc_u32 s81, s61, 0
	s_mov_b32 s82, -2
	v_mov_b32_e32 v1, v0
	v_mov_b64_e32 v[2:3], 0
	v_mov_b64_e32 v[4:5], 0
	v_mov_b64_e32 v[6:7], 0
	v_mov_b64_e32 v[8:9], 0
	v_mov_b64_e32 v[10:11], 0
	v_mov_b64_e32 v[16:17], 0
	v_mov_b64_e32 v[18:19], 0
	v_mov_b64_e32 v[24:25], 0
	v_mov_b64_e32 v[26:27], 0
	v_mov_b64_e32 v[32:33], 0
	v_mov_b64_e32 v[34:35], 0
	v_mov_b64_e32 v[40:41], 0
	v_mov_b64_e32 v[42:43], 0
	v_mov_b64_e32 v[48:49], 0
	v_mov_b64_e32 v[50:51], 0
	v_mov_b64_e32 v[12:13], 0
	v_mov_b64_e32 v[14:15], 0
	v_mov_b64_e32 v[20:21], 0
	v_mov_b64_e32 v[22:23], 0
	v_mov_b64_e32 v[28:29], 0
	v_mov_b64_e32 v[30:31], 0
	v_mov_b64_e32 v[36:37], 0
	v_mov_b64_e32 v[38:39], 0
	v_mov_b64_e32 v[44:45], 0
	v_mov_b64_e32 v[46:47], 0
	v_mov_b64_e32 v[52:53], 0
	v_mov_b64_e32 v[54:55], 0
	v_mov_b64_e32 v[56:57], 0
	v_mov_b64_e32 v[58:59], 0
	v_mov_b64_e32 v[60:61], 0
	v_mov_b64_e32 v[62:63], 0
	v_mov_b64_e32 v[64:65], 0
	v_mov_b64_e32 v[66:67], 0
	v_mov_b64_e32 v[68:69], 0
	v_mov_b64_e32 v[70:71], 0
	v_mov_b64_e32 v[72:73], 0
	v_mov_b64_e32 v[74:75], 0
	v_mov_b64_e32 v[80:81], 0
	v_mov_b64_e32 v[82:83], 0
	v_mov_b64_e32 v[88:89], 0
	v_mov_b64_e32 v[90:91], 0
	v_mov_b64_e32 v[96:97], 0
	v_mov_b64_e32 v[98:99], 0
	v_mov_b64_e32 v[104:105], 0
	v_mov_b64_e32 v[106:107], 0
	v_mov_b64_e32 v[112:113], 0
	v_mov_b64_e32 v[114:115], 0
	v_mov_b64_e32 v[76:77], 0
	v_mov_b64_e32 v[78:79], 0
	v_mov_b64_e32 v[84:85], 0
	v_mov_b64_e32 v[86:87], 0
	v_mov_b64_e32 v[92:93], 0
	v_mov_b64_e32 v[94:95], 0
	v_mov_b64_e32 v[100:101], 0
	v_mov_b64_e32 v[102:103], 0
	v_mov_b64_e32 v[108:109], 0
	v_mov_b64_e32 v[110:111], 0
	v_mov_b64_e32 v[116:117], 0
	v_mov_b64_e32 v[118:119], 0
	v_mov_b64_e32 v[120:121], 0
	v_mov_b64_e32 v[122:123], 0
	v_mov_b64_e32 v[124:125], 0
	v_mov_b64_e32 v[126:127], 0

.LBB0_1221:
	s_ashr_i32 s21, s20, 31
	s_lshl_b64 s[22:23], s[20:21], 17
	s_add_u32 s22, s70, s22
	s_addc_u32 s23, s71, s23
	s_and_b64 s[24:25], s[0:1], exec
	s_cselect_b32 s21, s23, s31
	s_cselect_b32 s55, s22, s30
	s_ashr_i32 s19, s18, 31
	s_lshl_b64 s[24:25], s[18:19], 17
	s_add_u32 s24, s53, s24
	s_addc_u32 s25, s72, s25
	s_and_b64 s[34:35], s[0:1], exec
	v_mov_b32_e32 v0, 0
	s_cselect_b32 s19, s25, s29
	s_cselect_b32 s85, s24, s28
	s_mov_b32 s60, 0
	s_mov_b64 s[34:35], -1
	s_mov_b64 s[42:43], 0
	v_mov_b32_e32 v1, v0
	v_mov_b64_e32 v[2:3], 0
	v_mov_b64_e32 v[4:5], 0
	v_mov_b64_e32 v[6:7], 0
	v_mov_b64_e32 v[8:9], 0
	v_mov_b64_e32 v[10:11], 0
	v_mov_b64_e32 v[16:17], 0
	v_mov_b64_e32 v[18:19], 0
	v_mov_b64_e32 v[24:25], 0
	v_mov_b64_e32 v[26:27], 0
	v_mov_b64_e32 v[32:33], 0
	v_mov_b64_e32 v[34:35], 0
	v_mov_b64_e32 v[40:41], 0
	v_mov_b64_e32 v[42:43], 0
	v_mov_b64_e32 v[48:49], 0
	v_mov_b64_e32 v[50:51], 0
	v_mov_b64_e32 v[12:13], 0
	v_mov_b64_e32 v[14:15], 0
	v_mov_b64_e32 v[20:21], 0
	v_mov_b64_e32 v[22:23], 0
	v_mov_b64_e32 v[28:29], 0
	v_mov_b64_e32 v[30:31], 0
	v_mov_b64_e32 v[36:37], 0
	v_mov_b64_e32 v[38:39], 0
	v_mov_b64_e32 v[44:45], 0
	v_mov_b64_e32 v[46:47], 0
	v_mov_b64_e32 v[52:53], 0
	v_mov_b64_e32 v[54:55], 0
	v_mov_b64_e32 v[56:57], 0
	v_mov_b64_e32 v[58:59], 0
	v_mov_b64_e32 v[60:61], 0
	v_mov_b64_e32 v[62:63], 0
	v_mov_b64_e32 v[64:65], 0
	v_mov_b64_e32 v[66:67], 0
	v_mov_b64_e32 v[68:69], 0
	v_mov_b64_e32 v[70:71], 0
	v_mov_b64_e32 v[72:73], 0
	v_mov_b64_e32 v[74:75], 0
	v_mov_b64_e32 v[80:81], 0
	v_mov_b64_e32 v[82:83], 0
	v_mov_b64_e32 v[88:89], 0
	v_mov_b64_e32 v[90:91], 0
	v_mov_b64_e32 v[96:97], 0
	v_mov_b64_e32 v[98:99], 0
	v_mov_b64_e32 v[104:105], 0
	v_mov_b64_e32 v[106:107], 0
	v_mov_b64_e32 v[112:113], 0
	v_mov_b64_e32 v[114:115], 0
	v_mov_b64_e32 v[76:77], 0
	v_mov_b64_e32 v[78:79], 0
	v_mov_b64_e32 v[84:85], 0
	v_mov_b64_e32 v[86:87], 0
	v_mov_b64_e32 v[92:93], 0
	v_mov_b64_e32 v[94:95], 0
	v_mov_b64_e32 v[100:101], 0
	v_mov_b64_e32 v[102:103], 0
	v_mov_b64_e32 v[108:109], 0
	v_mov_b64_e32 v[110:111], 0
	v_mov_b64_e32 v[116:117], 0
	v_mov_b64_e32 v[118:119], 0
	v_mov_b64_e32 v[120:121], 0
	v_mov_b64_e32 v[122:123], 0
	v_mov_b64_e32 v[124:125], 0
	v_mov_b64_e32 v[126:127], 0

.LBB0_1245:
	s_ashr_i32 s21, s20, 31
	s_lshl_b64 s[22:23], s[20:21], 17
	s_add_u32 s22, s52, s22
	s_addc_u32 s23, s53, s23
	s_and_b64 s[24:25], s[0:1], exec
	s_cselect_b32 s21, s23, s31
	s_cselect_b32 s55, s22, s30
	s_ashr_i32 s19, s18, 31
	s_lshl_b64 s[24:25], s[18:19], 17
	s_add_u32 s24, s70, s24
	s_addc_u32 s25, s71, s25
	s_and_b64 s[34:35], s[0:1], exec
	v_mov_b32_e32 v0, 0
	s_cselect_b32 s19, s25, s29
	s_cselect_b32 s86, s24, s28
	s_mov_b32 s60, 0
	s_mov_b64 s[34:35], -1
	s_mov_b64 s[42:43], 0
	v_mov_b32_e32 v1, v0
	v_mov_b64_e32 v[2:3], 0
	v_mov_b64_e32 v[4:5], 0
	v_mov_b64_e32 v[6:7], 0
	v_mov_b64_e32 v[8:9], 0
	v_mov_b64_e32 v[10:11], 0
	v_mov_b64_e32 v[16:17], 0
	v_mov_b64_e32 v[18:19], 0
	v_mov_b64_e32 v[24:25], 0
	v_mov_b64_e32 v[26:27], 0
	v_mov_b64_e32 v[32:33], 0
	v_mov_b64_e32 v[34:35], 0
	v_mov_b64_e32 v[40:41], 0
	v_mov_b64_e32 v[42:43], 0
	v_mov_b64_e32 v[48:49], 0
	v_mov_b64_e32 v[50:51], 0
	v_mov_b64_e32 v[12:13], 0
	v_mov_b64_e32 v[14:15], 0
	v_mov_b64_e32 v[20:21], 0
	v_mov_b64_e32 v[22:23], 0
	v_mov_b64_e32 v[28:29], 0
	v_mov_b64_e32 v[30:31], 0
	v_mov_b64_e32 v[36:37], 0
	v_mov_b64_e32 v[38:39], 0
	v_mov_b64_e32 v[44:45], 0
	v_mov_b64_e32 v[46:47], 0
	v_mov_b64_e32 v[52:53], 0
	v_mov_b64_e32 v[54:55], 0
	v_mov_b64_e32 v[56:57], 0
	v_mov_b64_e32 v[58:59], 0
	v_mov_b64_e32 v[60:61], 0
	v_mov_b64_e32 v[62:63], 0
	v_mov_b64_e32 v[64:65], 0
	v_mov_b64_e32 v[66:67], 0
	v_mov_b64_e32 v[68:69], 0
	v_mov_b64_e32 v[70:71], 0
	v_mov_b64_e32 v[72:73], 0
	v_mov_b64_e32 v[74:75], 0
	v_mov_b64_e32 v[80:81], 0
	v_mov_b64_e32 v[82:83], 0
	v_mov_b64_e32 v[88:89], 0
	v_mov_b64_e32 v[90:91], 0
	v_mov_b64_e32 v[96:97], 0
	v_mov_b64_e32 v[98:99], 0
	v_mov_b64_e32 v[104:105], 0
	v_mov_b64_e32 v[106:107], 0
	v_mov_b64_e32 v[112:113], 0
	v_mov_b64_e32 v[114:115], 0
	v_mov_b64_e32 v[76:77], 0
	v_mov_b64_e32 v[78:79], 0
	v_mov_b64_e32 v[84:85], 0
	v_mov_b64_e32 v[86:87], 0
	v_mov_b64_e32 v[92:93], 0
	v_mov_b64_e32 v[94:95], 0
	v_mov_b64_e32 v[100:101], 0
	v_mov_b64_e32 v[102:103], 0
	v_mov_b64_e32 v[108:109], 0
	v_mov_b64_e32 v[110:111], 0
	v_mov_b64_e32 v[116:117], 0
	v_mov_b64_e32 v[118:119], 0
	v_mov_b64_e32 v[120:121], 0
	v_mov_b64_e32 v[122:123], 0
	v_mov_b64_e32 v[124:125], 0
	v_mov_b64_e32 v[126:127], 0

.LBB0_1265:
	s_add_u32 s65, s18, 0x100
	v_mov_b32_e32 v0, 0
	s_addc_u32 s66, s19, 0
	s_mov_b32 s67, -2
	v_mov_b32_e32 v1, v0
	v_mov_b64_e32 v[2:3], 0
	v_mov_b64_e32 v[4:5], 0
	v_mov_b64_e32 v[6:7], 0
	v_mov_b64_e32 v[8:9], 0
	v_mov_b64_e32 v[10:11], 0
	v_mov_b64_e32 v[16:17], 0
	v_mov_b64_e32 v[18:19], 0
	v_mov_b64_e32 v[24:25], 0
	v_mov_b64_e32 v[26:27], 0
	v_mov_b64_e32 v[32:33], 0
	v_mov_b64_e32 v[34:35], 0
	v_mov_b64_e32 v[40:41], 0
	v_mov_b64_e32 v[42:43], 0
	v_mov_b64_e32 v[48:49], 0
	v_mov_b64_e32 v[50:51], 0
	v_mov_b64_e32 v[12:13], 0
	v_mov_b64_e32 v[14:15], 0
	v_mov_b64_e32 v[20:21], 0
	v_mov_b64_e32 v[22:23], 0
	v_mov_b64_e32 v[28:29], 0
	v_mov_b64_e32 v[30:31], 0
	v_mov_b64_e32 v[36:37], 0
	v_mov_b64_e32 v[38:39], 0
	v_mov_b64_e32 v[44:45], 0
	v_mov_b64_e32 v[46:47], 0
	v_mov_b64_e32 v[52:53], 0
	v_mov_b64_e32 v[54:55], 0
	v_mov_b64_e32 v[56:57], 0
	v_mov_b64_e32 v[58:59], 0
	v_mov_b64_e32 v[60:61], 0
	v_mov_b64_e32 v[62:63], 0
	v_mov_b64_e32 v[64:65], 0
	v_mov_b64_e32 v[66:67], 0
	v_mov_b64_e32 v[68:69], 0
	v_mov_b64_e32 v[70:71], 0
	v_mov_b64_e32 v[72:73], 0
	v_mov_b64_e32 v[74:75], 0
	v_mov_b64_e32 v[80:81], 0
	v_mov_b64_e32 v[82:83], 0
	v_mov_b64_e32 v[88:89], 0
	v_mov_b64_e32 v[90:91], 0
	v_mov_b64_e32 v[96:97], 0
	v_mov_b64_e32 v[98:99], 0
	v_mov_b64_e32 v[104:105], 0
	v_mov_b64_e32 v[106:107], 0
	v_mov_b64_e32 v[112:113], 0
	v_mov_b64_e32 v[114:115], 0
	v_mov_b64_e32 v[76:77], 0
	v_mov_b64_e32 v[78:79], 0
	v_mov_b64_e32 v[84:85], 0
	v_mov_b64_e32 v[86:87], 0
	v_mov_b64_e32 v[92:93], 0
	v_mov_b64_e32 v[94:95], 0
	v_mov_b64_e32 v[100:101], 0
	v_mov_b64_e32 v[102:103], 0
	v_mov_b64_e32 v[108:109], 0
	v_mov_b64_e32 v[110:111], 0
	v_mov_b64_e32 v[116:117], 0
	v_mov_b64_e32 v[118:119], 0
	v_mov_b64_e32 v[120:121], 0
	v_mov_b64_e32 v[122:123], 0
	v_mov_b64_e32 v[124:125], 0
	v_mov_b64_e32 v[126:127], 0

.LBB0_1433:
	s_ashr_i32 s23, s22, 31
	s_lshl_b64 s[24:25], s[22:23], 19
	s_add_u32 s24, s56, s24
	s_addc_u32 s25, s57, s25
	s_and_b64 s[26:27], s[0:1], exec
	s_cselect_b32 s23, s25, s31
	s_cselect_b32 s55, s24, s30
	s_ashr_i32 s21, s20, 31
	s_lshl_b64 s[26:27], s[20:21], 19
	s_add_u32 s26, s53, s26
	s_addc_u32 s27, s60, s27
	s_and_b64 s[42:43], s[0:1], exec
	s_cselect_b32 s21, s27, s35
	s_cselect_b32 s74, s26, s34
	s_add_u32 s30, s30, 0x40080
	s_addc_u32 s31, s31, 0
	s_add_u32 s75, s34, 0x100
	v_mov_b32_e32 v0, 0
	s_addc_u32 s76, s35, 0
	s_mov_b32 s77, -2
	v_mov_b32_e32 v1, v0
	v_mov_b64_e32 v[2:3], 0
	v_mov_b64_e32 v[4:5], 0
	v_mov_b64_e32 v[6:7], 0
	v_mov_b64_e32 v[8:9], 0
	v_mov_b64_e32 v[10:11], 0
	v_mov_b64_e32 v[16:17], 0
	v_mov_b64_e32 v[18:19], 0
	v_mov_b64_e32 v[24:25], 0
	v_mov_b64_e32 v[26:27], 0
	v_mov_b64_e32 v[32:33], 0
	v_mov_b64_e32 v[34:35], 0
	v_mov_b64_e32 v[40:41], 0
	v_mov_b64_e32 v[42:43], 0
	v_mov_b64_e32 v[48:49], 0
	v_mov_b64_e32 v[50:51], 0
	v_mov_b64_e32 v[12:13], 0
	v_mov_b64_e32 v[14:15], 0
	v_mov_b64_e32 v[20:21], 0
	v_mov_b64_e32 v[22:23], 0
	v_mov_b64_e32 v[28:29], 0
	v_mov_b64_e32 v[30:31], 0
	v_mov_b64_e32 v[36:37], 0
	v_mov_b64_e32 v[38:39], 0
	v_mov_b64_e32 v[44:45], 0
	v_mov_b64_e32 v[46:47], 0
	v_mov_b64_e32 v[52:53], 0
	v_mov_b64_e32 v[54:55], 0
	v_mov_b64_e32 v[56:57], 0
	v_mov_b64_e32 v[58:59], 0
	v_mov_b64_e32 v[60:61], 0
	v_mov_b64_e32 v[62:63], 0
	v_mov_b64_e32 v[64:65], 0
	v_mov_b64_e32 v[66:67], 0
	v_mov_b64_e32 v[68:69], 0
	v_mov_b64_e32 v[70:71], 0
	v_mov_b64_e32 v[72:73], 0
	v_mov_b64_e32 v[74:75], 0
	v_mov_b64_e32 v[80:81], 0
	v_mov_b64_e32 v[82:83], 0
	v_mov_b64_e32 v[88:89], 0
	v_mov_b64_e32 v[90:91], 0
	v_mov_b64_e32 v[96:97], 0
	v_mov_b64_e32 v[98:99], 0
	v_mov_b64_e32 v[104:105], 0
	v_mov_b64_e32 v[106:107], 0
	v_mov_b64_e32 v[112:113], 0
	v_mov_b64_e32 v[114:115], 0
	v_mov_b64_e32 v[76:77], 0
	v_mov_b64_e32 v[78:79], 0
	v_mov_b64_e32 v[84:85], 0
	v_mov_b64_e32 v[86:87], 0
	v_mov_b64_e32 v[92:93], 0
	v_mov_b64_e32 v[94:95], 0
	v_mov_b64_e32 v[100:101], 0
	v_mov_b64_e32 v[102:103], 0
	v_mov_b64_e32 v[108:109], 0
	v_mov_b64_e32 v[110:111], 0
	v_mov_b64_e32 v[116:117], 0
	v_mov_b64_e32 v[118:119], 0
	v_mov_b64_e32 v[120:121], 0
	v_mov_b64_e32 v[122:123], 0
	v_mov_b64_e32 v[124:125], 0
	v_mov_b64_e32 v[126:127], 0

.LBB0_1570:
	s_ashr_i32 s23, s22, 31
	s_lshl_b64 s[24:25], s[22:23], 19
	s_add_u32 s24, s58, s24
	s_addc_u32 s25, s59, s25
	s_and_b64 s[26:27], s[0:1], exec
	s_cselect_b32 s23, s25, s31
	s_cselect_b32 s54, s24, s30
	s_ashr_i32 s21, s20, 31
	s_lshl_b64 s[26:27], s[20:21], 19
	s_add_u32 s26, s61, s26
	s_addc_u32 s27, s62, s27
	s_and_b64 s[42:43], s[0:1], exec
	s_cselect_b32 s21, s27, s35
	s_cselect_b32 s55, s26, s34
	s_add_u32 s30, s30, 0x40080
	s_addc_u32 s31, s31, 0
	s_add_u32 s75, s34, 0x100
	v_mov_b32_e32 v0, 0
	s_addc_u32 s76, s35, 0
	s_mov_b32 s77, -2
	v_mov_b32_e32 v1, v0
	v_mov_b64_e32 v[2:3], 0
	v_mov_b64_e32 v[4:5], 0
	v_mov_b64_e32 v[6:7], 0
	v_mov_b64_e32 v[16:17], 0
	v_mov_b64_e32 v[18:19], 0
	v_mov_b64_e32 v[20:21], 0
	v_mov_b64_e32 v[22:23], 0
	v_mov_b64_e32 v[32:33], 0
	v_mov_b64_e32 v[34:35], 0
	v_mov_b64_e32 v[36:37], 0
	v_mov_b64_e32 v[38:39], 0
	v_mov_b64_e32 v[48:49], 0
	v_mov_b64_e32 v[50:51], 0
	v_mov_b64_e32 v[52:53], 0
	v_mov_b64_e32 v[54:55], 0
	v_mov_b64_e32 v[8:9], 0
	v_mov_b64_e32 v[10:11], 0
	v_mov_b64_e32 v[12:13], 0
	v_mov_b64_e32 v[14:15], 0
	v_mov_b64_e32 v[24:25], 0
	v_mov_b64_e32 v[26:27], 0
	v_mov_b64_e32 v[28:29], 0
	v_mov_b64_e32 v[30:31], 0
	v_mov_b64_e32 v[40:41], 0
	v_mov_b64_e32 v[42:43], 0
	v_mov_b64_e32 v[44:45], 0
	v_mov_b64_e32 v[46:47], 0
	v_mov_b64_e32 v[56:57], 0
	v_mov_b64_e32 v[58:59], 0
	v_mov_b64_e32 v[60:61], 0
	v_mov_b64_e32 v[62:63], 0
	v_mov_b64_e32 v[64:65], 0
	v_mov_b64_e32 v[66:67], 0
	v_mov_b64_e32 v[68:69], 0
	v_mov_b64_e32 v[70:71], 0
	v_mov_b64_e32 v[80:81], 0
	v_mov_b64_e32 v[82:83], 0
	v_mov_b64_e32 v[84:85], 0
	v_mov_b64_e32 v[86:87], 0
	v_mov_b64_e32 v[96:97], 0
	v_mov_b64_e32 v[98:99], 0
	v_mov_b64_e32 v[100:101], 0
	v_mov_b64_e32 v[102:103], 0
	v_mov_b64_e32 v[112:113], 0
	v_mov_b64_e32 v[114:115], 0
	v_mov_b64_e32 v[116:117], 0
	v_mov_b64_e32 v[118:119], 0
	v_mov_b64_e32 v[72:73], 0
	v_mov_b64_e32 v[74:75], 0
	v_mov_b64_e32 v[76:77], 0
	v_mov_b64_e32 v[78:79], 0
	v_mov_b64_e32 v[88:89], 0
	v_mov_b64_e32 v[90:91], 0
	v_mov_b64_e32 v[92:93], 0
	v_mov_b64_e32 v[94:95], 0
	v_mov_b64_e32 v[104:105], 0
	v_mov_b64_e32 v[106:107], 0
	v_mov_b64_e32 v[108:109], 0
	v_mov_b64_e32 v[110:111], 0
	v_mov_b64_e32 v[120:121], 0
	v_mov_b64_e32 v[122:123], 0
	v_mov_b64_e32 v[124:125], 0
	v_mov_b64_e32 v[126:127], 0

.LBB0_1649:
	s_ashr_i32 s23, s22, 31
	s_lshl_b64 s[24:25], s[22:23], 21
	s_add_u32 s24, s56, s24
	s_addc_u32 s25, s57, s25
	s_and_b64 s[26:27], s[0:1], exec
	s_cselect_b32 s23, s25, s31
	s_cselect_b32 s55, s24, s30
	s_ashr_i32 s21, s20, 31
	s_lshl_b64 s[26:27], s[20:21], 21
	s_add_u32 s26, s53, s26
	s_addc_u32 s27, s58, s27
	s_and_b64 s[42:43], s[0:1], exec
	s_cselect_b32 s21, s27, s35
	s_cselect_b32 s72, s26, s34
	s_add_u32 s30, s30, 0x100080
	s_addc_u32 s31, s31, 0
	s_add_u32 s73, s34, 0x100
	v_mov_b32_e32 v0, 0
	s_addc_u32 s74, s35, 0
	s_mov_b32 s75, -2
	v_mov_b32_e32 v1, v0
	v_mov_b64_e32 v[2:3], 0
	v_mov_b64_e32 v[4:5], 0
	v_mov_b64_e32 v[6:7], 0
	v_mov_b64_e32 v[8:9], 0
	v_mov_b64_e32 v[10:11], 0
	v_mov_b64_e32 v[16:17], 0
	v_mov_b64_e32 v[18:19], 0
	v_mov_b64_e32 v[24:25], 0
	v_mov_b64_e32 v[26:27], 0
	v_mov_b64_e32 v[32:33], 0
	v_mov_b64_e32 v[34:35], 0
	v_mov_b64_e32 v[40:41], 0
	v_mov_b64_e32 v[42:43], 0
	v_mov_b64_e32 v[48:49], 0
	v_mov_b64_e32 v[50:51], 0
	v_mov_b64_e32 v[12:13], 0
	v_mov_b64_e32 v[14:15], 0
	v_mov_b64_e32 v[20:21], 0
	v_mov_b64_e32 v[22:23], 0
	v_mov_b64_e32 v[28:29], 0
	v_mov_b64_e32 v[30:31], 0
	v_mov_b64_e32 v[36:37], 0
	v_mov_b64_e32 v[38:39], 0
	v_mov_b64_e32 v[44:45], 0
	v_mov_b64_e32 v[46:47], 0
	v_mov_b64_e32 v[52:53], 0
	v_mov_b64_e32 v[54:55], 0
	v_mov_b64_e32 v[56:57], 0
	v_mov_b64_e32 v[58:59], 0
	v_mov_b64_e32 v[60:61], 0
	v_mov_b64_e32 v[62:63], 0
	v_mov_b64_e32 v[64:65], 0
	v_mov_b64_e32 v[66:67], 0
	v_mov_b64_e32 v[68:69], 0
	v_mov_b64_e32 v[70:71], 0
	v_mov_b64_e32 v[72:73], 0
	v_mov_b64_e32 v[74:75], 0
	v_mov_b64_e32 v[80:81], 0
	v_mov_b64_e32 v[82:83], 0
	v_mov_b64_e32 v[88:89], 0
	v_mov_b64_e32 v[90:91], 0
	v_mov_b64_e32 v[96:97], 0
	v_mov_b64_e32 v[98:99], 0
	v_mov_b64_e32 v[104:105], 0
	v_mov_b64_e32 v[106:107], 0
	v_mov_b64_e32 v[112:113], 0
	v_mov_b64_e32 v[114:115], 0
	v_mov_b64_e32 v[76:77], 0
	v_mov_b64_e32 v[78:79], 0
	v_mov_b64_e32 v[84:85], 0
	v_mov_b64_e32 v[86:87], 0
	v_mov_b64_e32 v[92:93], 0
	v_mov_b64_e32 v[94:95], 0
	v_mov_b64_e32 v[100:101], 0
	v_mov_b64_e32 v[102:103], 0
	v_mov_b64_e32 v[108:109], 0
	v_mov_b64_e32 v[110:111], 0
	v_mov_b64_e32 v[116:117], 0
	v_mov_b64_e32 v[118:119], 0
	v_mov_b64_e32 v[120:121], 0
	v_mov_b64_e32 v[122:123], 0
	v_mov_b64_e32 v[124:125], 0
	v_mov_b64_e32 v[126:127], 0
